# thin_gemm K loop issues 8 k-steps of loads before first MFMA with counted vmcnt (was load-wait-mfma serial); plus attention item balance, gnorm fast path, xcd first seam
# speedup vs baseline: 1.0228x; 1.0109x over previous
.LBB0_80:
	s_waitcnt vmcnt(0)
	v_lshlrev_b32_e32 v96, 16, v44
	s_mov_b32 s5, 0xffff
	v_lshlrev_b32_e32 v100, 16, v45
	s_waitcnt vmcnt(2)
	v_and_or_b32 v96, v24, s5, v96
	v_and_or_b32 v100, v25, s5, v100
	v_add_u32_e32 v101, 0x8800, v158
	ds_write_b128 v205, v[0:3]
	ds_write_b128 v206, v[4:7]
	ds_write_b128 v207, v[8:11]
	ds_write_b128 v208, v[12:15]
	v_lshrrev_b32_e32 v97, 16, v24
	s_mov_b32 s4, 0xffff0000
	ds_write2_b32 v101, v96, v100 offset1:136
	v_lshrrev_b32_e32 v96, 16, v25
	v_and_or_b32 v97, v44, s4, v97
	v_and_or_b32 v96, v45, s4, v96
	v_add_u32_e32 v100, 0x8800, v159
	ds_write2_b32 v100, v97, v96 offset0:68 offset1:204
	v_lshlrev_b32_e32 v96, 16, v46
	v_lshlrev_b32_e32 v100, 16, v47
	v_and_or_b32 v96, v26, s5, v96
	v_and_or_b32 v100, v27, s5, v100
	v_add_u32_e32 v101, 0x8c00, v158
	v_lshrrev_b32_e32 v97, 16, v26
	ds_write2_b32 v101, v96, v100 offset0:16 offset1:152
	v_lshrrev_b32_e32 v96, 16, v27
	v_and_or_b32 v97, v46, s4, v97
	v_and_or_b32 v96, v47, s4, v96
	v_add_u32_e32 v100, 0x8c00, v159
	ds_write2_b32 v100, v97, v96 offset0:84 offset1:220
	v_lshlrev_b32_e32 v96, 16, v40
	v_lshlrev_b32_e32 v100, 16, v41
	v_and_or_b32 v96, v16, s5, v96
	v_and_or_b32 v100, v17, s5, v100
	v_add_u32_e32 v101, 0x9000, v158
	v_lshrrev_b32_e32 v97, 16, v16
	ds_write2_b32 v101, v96, v100 offset0:32 offset1:168
	v_lshrrev_b32_e32 v96, 16, v17
	v_and_or_b32 v97, v40, s4, v97
	v_and_or_b32 v96, v41, s4, v96
	v_add_u32_e32 v100, 0x9000, v159
	ds_write2_b32 v100, v97, v96 offset0:100 offset1:236
	v_lshlrev_b32_e32 v96, 16, v42
	v_lshlrev_b32_e32 v100, 16, v43
	v_and_or_b32 v96, v18, s5, v96
	v_and_or_b32 v100, v19, s5, v100
	v_add_u32_e32 v101, 0x9400, v158
	v_lshrrev_b32_e32 v97, 16, v18
	ds_write2_b32 v101, v96, v100 offset0:48 offset1:184
	v_lshrrev_b32_e32 v96, 16, v19
	v_and_or_b32 v97, v42, s4, v97
	v_and_or_b32 v96, v43, s4, v96
	v_add_u32_e32 v100, 0x9400, v159
	s_cmp_ge_i32 s20, s42
	s_mov_b64 s[4:5], -1
	ds_write2_b32 v100, v97, v96 offset0:116 offset1:252
	s_waitcnt lgkmcnt(0)
	s_barrier
	s_cbranch_scc0 .LBB0_92
	s_load_dword s4, s[74:75], 0x0
	s_mov_b64 s[58:59], -1
	s_mov_b32 s28, s20
	s_mov_b32 s15, s42
	s_mov_b32 s17, s50
	s_waitcnt lgkmcnt(0)
	s_add_i32 s11, s4, s43
	s_cmpk_gt_i32 s11, 0x5ff
	s_mov_b32 s29, s52
	s_mov_b32 s56, s46
	s_mov_b32 s30, s1
	s_cbranch_scc1 .LBB0_91
	s_bfe_u32 s98, s11, 0x10008
	s_xor_b32 s98, s11, s98
	s_mul_hi_i32 s4, s98, 0x2aaaaaab
	s_lshr_b32 s5, s4, 31
	s_ashr_i32 s6, s4, 4
	s_add_i32 s6, s6, s5
	s_mul_i32 s4, s6, 0x60
	s_sub_i32 s15, s98, s4
	s_cmp_lt_i32 s15, 32
	s_cbranch_scc1 .LBB0_87
	s_cmp_gt_u32 s15, 63
	s_mov_b64 s[4:5], -1
	s_cbranch_scc0 .LBB0_85
	s_sub_i32 s4, s15, 64
	s_lshr_b32 s7, s4, 1
	s_and_b32 s28, s15, 1
	s_mov_b64 s[4:5], 0

.LBB0_112:
	v_readlane_b32 s0, v254, 0
	s_load_dword s99, s[74:75], 0x0
	s_waitcnt lgkmcnt(0)
	s_cmpk_eq_i32 s99, 0x100
	s_cbranch_scc0 .Lsamp_orig
	s_and_b32 s98, s0, 6
	s_cmp_lg_u32 s98, 0
	s_cbranch_scc1 .LBB0_171
	s_lshr_b32 s98, s0, 3
	s_lshl_b32 s98, s98, 1
	s_and_b32 s0, s0, 1
	s_or_b32 s0, s0, s98
.Lsamp_orig:
	s_cmp_gt_i32 s0, 63
	s_cbranch_scc1 .LBB0_171
	s_load_dwordx2 s[4:5], s[68:69], 0xc0
	s_load_dwordx4 s[44:47], s[68:69], 0x20
	s_add_u32 s1, s24, 0x21a59800
	s_addc_u32 s2, s25, 0
	s_waitcnt lgkmcnt(0)
	s_add_u32 s10, s4, 0x74c4000
	s_addc_u32 s11, s5, 0
	s_add_u32 s15, s4, 0x74cc000
	s_addc_u32 s17, s5, 0
	s_branch .LBB0_115

.Lgn_top:
	s_mul_i32 s4, s2, 3
	s_add_i32 s4, s4, s26
	s_cmpk_gt_i32 s4, 0x1fff
	s_cbranch_scc1 .Lgn_exit
	v_mov_b32_e32 v202, 0x5200
	s_mov_b64 s[6:7], 0x1000
	s_mov_b32 s4, s26
	v_mad_i64_i32 v[6:7], s[40:41], s4, v202, v[4:5]
	s_lshl_b32 s5, s4, 5
	s_add_u32 s42, s0, s5
	s_addc_u32 s43, s1, 0
	v_lshl_add_u64 v[184:185], v[6:7], 0, s[6:7]
	global_load_dwordx4 v[40:43], v[6:7], off
	global_load_dwordx4 v[44:47], v[6:7], off offset:1024
	global_load_dwordx4 v[48:51], v[6:7], off offset:2048
	global_load_dwordx4 v[52:55], v[6:7], off offset:3072
	global_load_dwordx4 v[56:59], v[184:185], off
	global_load_dwordx4 v[60:63], v[184:185], off offset:1024
	global_load_dwordx4 v[64:67], v[184:185], off offset:2048
	global_load_dwordx4 v[68:71], v[184:185], off offset:3072
	global_load_dwordx4 v[8:11], v173, s[42:43]
	global_load_dwordx4 v[12:15], v173, s[42:43] offset:16
	s_add_i32 s4, s4, s2
	v_mad_i64_i32 v[20:21], s[40:41], s4, v202, v[4:5]
	s_lshl_b32 s5, s4, 5
	s_add_u32 s42, s0, s5
	s_addc_u32 s43, s1, 0
	v_lshl_add_u64 v[188:189], v[20:21], 0, s[6:7]
	global_load_dwordx4 v[72:75], v[20:21], off
	global_load_dwordx4 v[76:79], v[20:21], off offset:1024
	global_load_dwordx4 v[80:83], v[20:21], off offset:2048
	global_load_dwordx4 v[84:87], v[20:21], off offset:3072
	global_load_dwordx4 v[88:91], v[188:189], off
	global_load_dwordx4 v[92:95], v[188:189], off offset:1024
	global_load_dwordx4 v[96:99], v[188:189], off offset:2048
	global_load_dwordx4 v[100:103], v[188:189], off offset:3072
	global_load_dwordx4 v[16:19], v173, s[42:43]
	global_load_dwordx4 v[28:31], v173, s[42:43] offset:16
	s_add_i32 s4, s4, s2
	v_mad_i64_i32 v[182:183], s[40:41], s4, v202, v[4:5]
	s_lshl_b32 s5, s4, 5
	s_add_u32 s42, s0, s5
	s_addc_u32 s43, s1, 0
	v_lshl_add_u64 v[196:197], v[182:183], 0, s[6:7]
	global_load_dwordx4 v[104:107], v[182:183], off
	global_load_dwordx4 v[108:111], v[182:183], off offset:1024
	global_load_dwordx4 v[112:115], v[182:183], off offset:2048
	global_load_dwordx4 v[116:119], v[182:183], off offset:3072
	global_load_dwordx4 v[120:123], v[196:197], off
	global_load_dwordx4 v[124:127], v[196:197], off offset:1024
	global_load_dwordx4 v[128:131], v[196:197], off offset:2048
	global_load_dwordx4 v[132:135], v[196:197], off offset:3072
	global_load_dwordx4 v[32:35], v173, s[42:43]
	global_load_dwordx4 v[36:39], v173, s[42:43] offset:16
	s_add_i32 s4, s4, s2
	v_mad_i64_i32 v[186:187], s[40:41], s4, v202, v[4:5]
	s_lshl_b32 s5, s4, 5
	s_add_u32 s42, s0, s5
	s_addc_u32 s43, s1, 0
	v_lshl_add_u64 v[198:199], v[186:187], 0, s[6:7]
	global_load_dwordx4 v[136:139], v[186:187], off
	global_load_dwordx4 v[140:143], v[186:187], off offset:1024
	global_load_dwordx4 v[144:147], v[186:187], off offset:2048
	global_load_dwordx4 v[148:151], v[186:187], off offset:3072
	global_load_dwordx4 v[152:155], v[198:199], off
	global_load_dwordx4 v[156:159], v[198:199], off offset:1024
	global_load_dwordx4 v[160:163], v[198:199], off offset:2048
	global_load_dwordx4 v[164:167], v[198:199], off offset:3072
	global_load_dwordx4 v[0:3], v173, s[42:43]
	global_load_dwordx4 v[168:171], v173, s[42:43] offset:16
	s_waitcnt vmcnt(30)
	v_lshlrev_b32_e32 v200, 16, v40
	v_and_b32_e32 v201, 0xffff0000, v40
	v_mul_f32_e32 v200, v8, v200
	v_mul_f32_e32 v201, v8, v201
	v_cvt_pk_bf16_f32 v40, v200, v201
	v_lshlrev_b32_e32 v200, 16, v41
	v_and_b32_e32 v201, 0xffff0000, v41
	v_mul_f32_e32 v200, v8, v200
	v_mul_f32_e32 v201, v8, v201
	v_cvt_pk_bf16_f32 v41, v200, v201
	v_lshlrev_b32_e32 v200, 16, v42
	v_and_b32_e32 v201, 0xffff0000, v42
	v_mul_f32_e32 v200, v8, v200
	v_mul_f32_e32 v201, v8, v201
	v_cvt_pk_bf16_f32 v42, v200, v201
	v_lshlrev_b32_e32 v200, 16, v43
	v_and_b32_e32 v201, 0xffff0000, v43
	v_mul_f32_e32 v200, v8, v200
	v_mul_f32_e32 v201, v8, v201
	v_cvt_pk_bf16_f32 v43, v200, v201
	global_store_dwordx4 v[6:7], v[40:43], off
	v_lshlrev_b32_e32 v200, 16, v44
	v_and_b32_e32 v201, 0xffff0000, v44
	v_mul_f32_e32 v200, v9, v200
	v_mul_f32_e32 v201, v9, v201
	v_cvt_pk_bf16_f32 v44, v200, v201
	v_lshlrev_b32_e32 v200, 16, v45
	v_and_b32_e32 v201, 0xffff0000, v45
	v_mul_f32_e32 v200, v9, v200
	v_mul_f32_e32 v201, v9, v201
	v_cvt_pk_bf16_f32 v45, v200, v201
	v_lshlrev_b32_e32 v200, 16, v46
	v_and_b32_e32 v201, 0xffff0000, v46
	v_mul_f32_e32 v200, v9, v200
	v_mul_f32_e32 v201, v9, v201
	v_cvt_pk_bf16_f32 v46, v200, v201
	v_lshlrev_b32_e32 v200, 16, v47
	v_and_b32_e32 v201, 0xffff0000, v47
	v_mul_f32_e32 v200, v9, v200
	v_mul_f32_e32 v201, v9, v201
	v_cvt_pk_bf16_f32 v47, v200, v201
	global_store_dwordx4 v[6:7], v[44:47], off offset:1024
	v_lshlrev_b32_e32 v200, 16, v48
	v_and_b32_e32 v201, 0xffff0000, v48
	v_mul_f32_e32 v200, v10, v200
	v_mul_f32_e32 v201, v10, v201
	v_cvt_pk_bf16_f32 v48, v200, v201
	v_lshlrev_b32_e32 v200, 16, v49
	v_and_b32_e32 v201, 0xffff0000, v49
	v_mul_f32_e32 v200, v10, v200
	v_mul_f32_e32 v201, v10, v201
	v_cvt_pk_bf16_f32 v49, v200, v201
	v_lshlrev_b32_e32 v200, 16, v50
	v_and_b32_e32 v201, 0xffff0000, v50
	v_mul_f32_e32 v200, v10, v200
	v_mul_f32_e32 v201, v10, v201
	v_cvt_pk_bf16_f32 v50, v200, v201
	v_lshlrev_b32_e32 v200, 16, v51
	v_and_b32_e32 v201, 0xffff0000, v51
	v_mul_f32_e32 v200, v10, v200
	v_mul_f32_e32 v201, v10, v201
	v_cvt_pk_bf16_f32 v51, v200, v201
	global_store_dwordx4 v[6:7], v[48:51], off offset:2048
	v_lshlrev_b32_e32 v200, 16, v52
	v_and_b32_e32 v201, 0xffff0000, v52
	v_mul_f32_e32 v200, v11, v200
	v_mul_f32_e32 v201, v11, v201
	v_cvt_pk_bf16_f32 v52, v200, v201
	v_lshlrev_b32_e32 v200, 16, v53
	v_and_b32_e32 v201, 0xffff0000, v53
	v_mul_f32_e32 v200, v11, v200
	v_mul_f32_e32 v201, v11, v201
	v_cvt_pk_bf16_f32 v53, v200, v201
	v_lshlrev_b32_e32 v200, 16, v54
	v_and_b32_e32 v201, 0xffff0000, v54
	v_mul_f32_e32 v200, v11, v200
	v_mul_f32_e32 v201, v11, v201
	v_cvt_pk_bf16_f32 v54, v200, v201
	v_lshlrev_b32_e32 v200, 16, v55
	v_and_b32_e32 v201, 0xffff0000, v55
	v_mul_f32_e32 v200, v11, v200
	v_mul_f32_e32 v201, v11, v201
	v_cvt_pk_bf16_f32 v55, v200, v201
	global_store_dwordx4 v[6:7], v[52:55], off offset:3072
	v_lshlrev_b32_e32 v200, 16, v56
	v_and_b32_e32 v201, 0xffff0000, v56
	v_mul_f32_e32 v200, v12, v200
	v_mul_f32_e32 v201, v12, v201
	v_cvt_pk_bf16_f32 v56, v200, v201
	v_lshlrev_b32_e32 v200, 16, v57
	v_and_b32_e32 v201, 0xffff0000, v57
	v_mul_f32_e32 v200, v12, v200
	v_mul_f32_e32 v201, v12, v201
	v_cvt_pk_bf16_f32 v57, v200, v201
	v_lshlrev_b32_e32 v200, 16, v58
	v_and_b32_e32 v201, 0xffff0000, v58
	v_mul_f32_e32 v200, v12, v200
	v_mul_f32_e32 v201, v12, v201
	v_cvt_pk_bf16_f32 v58, v200, v201
	v_lshlrev_b32_e32 v200, 16, v59
	v_and_b32_e32 v201, 0xffff0000, v59
	v_mul_f32_e32 v200, v12, v200
	v_mul_f32_e32 v201, v12, v201
	v_cvt_pk_bf16_f32 v59, v200, v201
	global_store_dwordx4 v[184:185], v[56:59], off
	v_lshlrev_b32_e32 v200, 16, v60
	v_and_b32_e32 v201, 0xffff0000, v60
	v_mul_f32_e32 v200, v13, v200
	v_mul_f32_e32 v201, v13, v201
	v_cvt_pk_bf16_f32 v60, v200, v201
	v_lshlrev_b32_e32 v200, 16, v61
	v_and_b32_e32 v201, 0xffff0000, v61
	v_mul_f32_e32 v200, v13, v200
	v_mul_f32_e32 v201, v13, v201
	v_cvt_pk_bf16_f32 v61, v200, v201
	v_lshlrev_b32_e32 v200, 16, v62
	v_and_b32_e32 v201, 0xffff0000, v62
	v_mul_f32_e32 v200, v13, v200
	v_mul_f32_e32 v201, v13, v201
	v_cvt_pk_bf16_f32 v62, v200, v201
	v_lshlrev_b32_e32 v200, 16, v63
	v_and_b32_e32 v201, 0xffff0000, v63
	v_mul_f32_e32 v200, v13, v200
	v_mul_f32_e32 v201, v13, v201
	v_cvt_pk_bf16_f32 v63, v200, v201
	global_store_dwordx4 v[184:185], v[60:63], off offset:1024
	v_lshlrev_b32_e32 v200, 16, v64
	v_and_b32_e32 v201, 0xffff0000, v64
	v_mul_f32_e32 v200, v14, v200
	v_mul_f32_e32 v201, v14, v201
	v_cvt_pk_bf16_f32 v64, v200, v201
	v_lshlrev_b32_e32 v200, 16, v65
	v_and_b32_e32 v201, 0xffff0000, v65
	v_mul_f32_e32 v200, v14, v200
	v_mul_f32_e32 v201, v14, v201
	v_cvt_pk_bf16_f32 v65, v200, v201
	v_lshlrev_b32_e32 v200, 16, v66
	v_and_b32_e32 v201, 0xffff0000, v66
	v_mul_f32_e32 v200, v14, v200
	v_mul_f32_e32 v201, v14, v201
	v_cvt_pk_bf16_f32 v66, v200, v201
	v_lshlrev_b32_e32 v200, 16, v67
	v_and_b32_e32 v201, 0xffff0000, v67
	v_mul_f32_e32 v200, v14, v200
	v_mul_f32_e32 v201, v14, v201
	v_cvt_pk_bf16_f32 v67, v200, v201
	global_store_dwordx4 v[184:185], v[64:67], off offset:2048
	v_lshlrev_b32_e32 v200, 16, v68
	v_and_b32_e32 v201, 0xffff0000, v68
	v_mul_f32_e32 v200, v15, v200
	v_mul_f32_e32 v201, v15, v201
	v_cvt_pk_bf16_f32 v68, v200, v201
	v_lshlrev_b32_e32 v200, 16, v69
	v_and_b32_e32 v201, 0xffff0000, v69
	v_mul_f32_e32 v200, v15, v200
	v_mul_f32_e32 v201, v15, v201
	v_cvt_pk_bf16_f32 v69, v200, v201
	v_lshlrev_b32_e32 v200, 16, v70
	v_and_b32_e32 v201, 0xffff0000, v70
	v_mul_f32_e32 v200, v15, v200
	v_mul_f32_e32 v201, v15, v201
	v_cvt_pk_bf16_f32 v70, v200, v201
	v_lshlrev_b32_e32 v200, 16, v71
	v_and_b32_e32 v201, 0xffff0000, v71
	v_mul_f32_e32 v200, v15, v200
	v_mul_f32_e32 v201, v15, v201
	v_cvt_pk_bf16_f32 v71, v200, v201
	global_store_dwordx4 v[184:185], v[68:71], off offset:3072
	s_waitcnt vmcnt(28)
	v_lshlrev_b32_e32 v200, 16, v72
	v_and_b32_e32 v201, 0xffff0000, v72
	v_mul_f32_e32 v200, v16, v200
	v_mul_f32_e32 v201, v16, v201
	v_cvt_pk_bf16_f32 v72, v200, v201
	v_lshlrev_b32_e32 v200, 16, v73
	v_and_b32_e32 v201, 0xffff0000, v73
	v_mul_f32_e32 v200, v16, v200
	v_mul_f32_e32 v201, v16, v201
	v_cvt_pk_bf16_f32 v73, v200, v201
	v_lshlrev_b32_e32 v200, 16, v74
	v_and_b32_e32 v201, 0xffff0000, v74
	v_mul_f32_e32 v200, v16, v200
	v_mul_f32_e32 v201, v16, v201
	v_cvt_pk_bf16_f32 v74, v200, v201
	v_lshlrev_b32_e32 v200, 16, v75
	v_and_b32_e32 v201, 0xffff0000, v75
	v_mul_f32_e32 v200, v16, v200
	v_mul_f32_e32 v201, v16, v201
	v_cvt_pk_bf16_f32 v75, v200, v201
	global_store_dwordx4 v[20:21], v[72:75], off
	v_lshlrev_b32_e32 v200, 16, v76
	v_and_b32_e32 v201, 0xffff0000, v76
	v_mul_f32_e32 v200, v17, v200
	v_mul_f32_e32 v201, v17, v201
	v_cvt_pk_bf16_f32 v76, v200, v201
	v_lshlrev_b32_e32 v200, 16, v77
	v_and_b32_e32 v201, 0xffff0000, v77
	v_mul_f32_e32 v200, v17, v200
	v_mul_f32_e32 v201, v17, v201
	v_cvt_pk_bf16_f32 v77, v200, v201
	v_lshlrev_b32_e32 v200, 16, v78
	v_and_b32_e32 v201, 0xffff0000, v78
	v_mul_f32_e32 v200, v17, v200
	v_mul_f32_e32 v201, v17, v201
	v_cvt_pk_bf16_f32 v78, v200, v201
	v_lshlrev_b32_e32 v200, 16, v79
	v_and_b32_e32 v201, 0xffff0000, v79
	v_mul_f32_e32 v200, v17, v200
	v_mul_f32_e32 v201, v17, v201
	v_cvt_pk_bf16_f32 v79, v200, v201
	global_store_dwordx4 v[20:21], v[76:79], off offset:1024
	v_lshlrev_b32_e32 v200, 16, v80
	v_and_b32_e32 v201, 0xffff0000, v80
	v_mul_f32_e32 v200, v18, v200
	v_mul_f32_e32 v201, v18, v201
	v_cvt_pk_bf16_f32 v80, v200, v201
	v_lshlrev_b32_e32 v200, 16, v81
	v_and_b32_e32 v201, 0xffff0000, v81
	v_mul_f32_e32 v200, v18, v200
	v_mul_f32_e32 v201, v18, v201
	v_cvt_pk_bf16_f32 v81, v200, v201
	v_lshlrev_b32_e32 v200, 16, v82
	v_and_b32_e32 v201, 0xffff0000, v82
	v_mul_f32_e32 v200, v18, v200
	v_mul_f32_e32 v201, v18, v201
	v_cvt_pk_bf16_f32 v82, v200, v201
	v_lshlrev_b32_e32 v200, 16, v83
	v_and_b32_e32 v201, 0xffff0000, v83
	v_mul_f32_e32 v200, v18, v200
	v_mul_f32_e32 v201, v18, v201
	v_cvt_pk_bf16_f32 v83, v200, v201
	global_store_dwordx4 v[20:21], v[80:83], off offset:2048
	v_lshlrev_b32_e32 v200, 16, v84
	v_and_b32_e32 v201, 0xffff0000, v84
	v_mul_f32_e32 v200, v19, v200
	v_mul_f32_e32 v201, v19, v201
	v_cvt_pk_bf16_f32 v84, v200, v201
	v_lshlrev_b32_e32 v200, 16, v85
	v_and_b32_e32 v201, 0xffff0000, v85
	v_mul_f32_e32 v200, v19, v200
	v_mul_f32_e32 v201, v19, v201
	v_cvt_pk_bf16_f32 v85, v200, v201
	v_lshlrev_b32_e32 v200, 16, v86
	v_and_b32_e32 v201, 0xffff0000, v86
	v_mul_f32_e32 v200, v19, v200
	v_mul_f32_e32 v201, v19, v201
	v_cvt_pk_bf16_f32 v86, v200, v201
	v_lshlrev_b32_e32 v200, 16, v87
	v_and_b32_e32 v201, 0xffff0000, v87
	v_mul_f32_e32 v200, v19, v200
	v_mul_f32_e32 v201, v19, v201
	v_cvt_pk_bf16_f32 v87, v200, v201
	global_store_dwordx4 v[20:21], v[84:87], off offset:3072
	v_lshlrev_b32_e32 v200, 16, v88
	v_and_b32_e32 v201, 0xffff0000, v88
	v_mul_f32_e32 v200, v28, v200
	v_mul_f32_e32 v201, v28, v201
	v_cvt_pk_bf16_f32 v88, v200, v201
	v_lshlrev_b32_e32 v200, 16, v89
	v_and_b32_e32 v201, 0xffff0000, v89
	v_mul_f32_e32 v200, v28, v200
	v_mul_f32_e32 v201, v28, v201
	v_cvt_pk_bf16_f32 v89, v200, v201
	v_lshlrev_b32_e32 v200, 16, v90
	v_and_b32_e32 v201, 0xffff0000, v90
	v_mul_f32_e32 v200, v28, v200
	v_mul_f32_e32 v201, v28, v201
	v_cvt_pk_bf16_f32 v90, v200, v201
	v_lshlrev_b32_e32 v200, 16, v91
	v_and_b32_e32 v201, 0xffff0000, v91
	v_mul_f32_e32 v200, v28, v200
	v_mul_f32_e32 v201, v28, v201
	v_cvt_pk_bf16_f32 v91, v200, v201
	global_store_dwordx4 v[188:189], v[88:91], off
	v_lshlrev_b32_e32 v200, 16, v92
	v_and_b32_e32 v201, 0xffff0000, v92
	v_mul_f32_e32 v200, v29, v200
	v_mul_f32_e32 v201, v29, v201
	v_cvt_pk_bf16_f32 v92, v200, v201
	v_lshlrev_b32_e32 v200, 16, v93
	v_and_b32_e32 v201, 0xffff0000, v93
	v_mul_f32_e32 v200, v29, v200
	v_mul_f32_e32 v201, v29, v201
	v_cvt_pk_bf16_f32 v93, v200, v201
	v_lshlrev_b32_e32 v200, 16, v94
	v_and_b32_e32 v201, 0xffff0000, v94
	v_mul_f32_e32 v200, v29, v200
	v_mul_f32_e32 v201, v29, v201
	v_cvt_pk_bf16_f32 v94, v200, v201
	v_lshlrev_b32_e32 v200, 16, v95
	v_and_b32_e32 v201, 0xffff0000, v95
	v_mul_f32_e32 v200, v29, v200
	v_mul_f32_e32 v201, v29, v201
	v_cvt_pk_bf16_f32 v95, v200, v201
	global_store_dwordx4 v[188:189], v[92:95], off offset:1024
	v_lshlrev_b32_e32 v200, 16, v96
	v_and_b32_e32 v201, 0xffff0000, v96
	v_mul_f32_e32 v200, v30, v200
	v_mul_f32_e32 v201, v30, v201
	v_cvt_pk_bf16_f32 v96, v200, v201
	v_lshlrev_b32_e32 v200, 16, v97
	v_and_b32_e32 v201, 0xffff0000, v97
	v_mul_f32_e32 v200, v30, v200
	v_mul_f32_e32 v201, v30, v201
	v_cvt_pk_bf16_f32 v97, v200, v201
	v_lshlrev_b32_e32 v200, 16, v98
	v_and_b32_e32 v201, 0xffff0000, v98
	v_mul_f32_e32 v200, v30, v200
	v_mul_f32_e32 v201, v30, v201
	v_cvt_pk_bf16_f32 v98, v200, v201
	v_lshlrev_b32_e32 v200, 16, v99
	v_and_b32_e32 v201, 0xffff0000, v99
	v_mul_f32_e32 v200, v30, v200
	v_mul_f32_e32 v201, v30, v201
	v_cvt_pk_bf16_f32 v99, v200, v201
	global_store_dwordx4 v[188:189], v[96:99], off offset:2048
	v_lshlrev_b32_e32 v200, 16, v100
	v_and_b32_e32 v201, 0xffff0000, v100
	v_mul_f32_e32 v200, v31, v200
	v_mul_f32_e32 v201, v31, v201
	v_cvt_pk_bf16_f32 v100, v200, v201
	v_lshlrev_b32_e32 v200, 16, v101
	v_and_b32_e32 v201, 0xffff0000, v101
	v_mul_f32_e32 v200, v31, v200
	v_mul_f32_e32 v201, v31, v201
	v_cvt_pk_bf16_f32 v101, v200, v201
	v_lshlrev_b32_e32 v200, 16, v102
	v_and_b32_e32 v201, 0xffff0000, v102
	v_mul_f32_e32 v200, v31, v200
	v_mul_f32_e32 v201, v31, v201
	v_cvt_pk_bf16_f32 v102, v200, v201
	v_lshlrev_b32_e32 v200, 16, v103
	v_and_b32_e32 v201, 0xffff0000, v103
	v_mul_f32_e32 v200, v31, v200
	v_mul_f32_e32 v201, v31, v201
	v_cvt_pk_bf16_f32 v103, v200, v201
	global_store_dwordx4 v[188:189], v[100:103], off offset:3072
	s_waitcnt vmcnt(26)
	v_lshlrev_b32_e32 v200, 16, v104
	v_and_b32_e32 v201, 0xffff0000, v104
	v_mul_f32_e32 v200, v32, v200
	v_mul_f32_e32 v201, v32, v201
	v_cvt_pk_bf16_f32 v104, v200, v201
	v_lshlrev_b32_e32 v200, 16, v105
	v_and_b32_e32 v201, 0xffff0000, v105
	v_mul_f32_e32 v200, v32, v200
	v_mul_f32_e32 v201, v32, v201
	v_cvt_pk_bf16_f32 v105, v200, v201
	v_lshlrev_b32_e32 v200, 16, v106
	v_and_b32_e32 v201, 0xffff0000, v106
	v_mul_f32_e32 v200, v32, v200
	v_mul_f32_e32 v201, v32, v201
	v_cvt_pk_bf16_f32 v106, v200, v201
	v_lshlrev_b32_e32 v200, 16, v107
	v_and_b32_e32 v201, 0xffff0000, v107
	v_mul_f32_e32 v200, v32, v200
	v_mul_f32_e32 v201, v32, v201
	v_cvt_pk_bf16_f32 v107, v200, v201
	global_store_dwordx4 v[182:183], v[104:107], off
	v_lshlrev_b32_e32 v200, 16, v108
	v_and_b32_e32 v201, 0xffff0000, v108
	v_mul_f32_e32 v200, v33, v200
	v_mul_f32_e32 v201, v33, v201
	v_cvt_pk_bf16_f32 v108, v200, v201
	v_lshlrev_b32_e32 v200, 16, v109
	v_and_b32_e32 v201, 0xffff0000, v109
	v_mul_f32_e32 v200, v33, v200
	v_mul_f32_e32 v201, v33, v201
	v_cvt_pk_bf16_f32 v109, v200, v201
	v_lshlrev_b32_e32 v200, 16, v110
	v_and_b32_e32 v201, 0xffff0000, v110
	v_mul_f32_e32 v200, v33, v200
	v_mul_f32_e32 v201, v33, v201
	v_cvt_pk_bf16_f32 v110, v200, v201
	v_lshlrev_b32_e32 v200, 16, v111
	v_and_b32_e32 v201, 0xffff0000, v111
	v_mul_f32_e32 v200, v33, v200
	v_mul_f32_e32 v201, v33, v201
	v_cvt_pk_bf16_f32 v111, v200, v201
	global_store_dwordx4 v[182:183], v[108:111], off offset:1024
	v_lshlrev_b32_e32 v200, 16, v112
	v_and_b32_e32 v201, 0xffff0000, v112
	v_mul_f32_e32 v200, v34, v200
	v_mul_f32_e32 v201, v34, v201
	v_cvt_pk_bf16_f32 v112, v200, v201
	v_lshlrev_b32_e32 v200, 16, v113
	v_and_b32_e32 v201, 0xffff0000, v113
	v_mul_f32_e32 v200, v34, v200
	v_mul_f32_e32 v201, v34, v201
	v_cvt_pk_bf16_f32 v113, v200, v201
	v_lshlrev_b32_e32 v200, 16, v114
	v_and_b32_e32 v201, 0xffff0000, v114
	v_mul_f32_e32 v200, v34, v200
	v_mul_f32_e32 v201, v34, v201
	v_cvt_pk_bf16_f32 v114, v200, v201
	v_lshlrev_b32_e32 v200, 16, v115
	v_and_b32_e32 v201, 0xffff0000, v115
	v_mul_f32_e32 v200, v34, v200
	v_mul_f32_e32 v201, v34, v201
	v_cvt_pk_bf16_f32 v115, v200, v201
	global_store_dwordx4 v[182:183], v[112:115], off offset:2048
	v_lshlrev_b32_e32 v200, 16, v116
	v_and_b32_e32 v201, 0xffff0000, v116
	v_mul_f32_e32 v200, v35, v200
	v_mul_f32_e32 v201, v35, v201
	v_cvt_pk_bf16_f32 v116, v200, v201
	v_lshlrev_b32_e32 v200, 16, v117
	v_and_b32_e32 v201, 0xffff0000, v117
	v_mul_f32_e32 v200, v35, v200
	v_mul_f32_e32 v201, v35, v201
	v_cvt_pk_bf16_f32 v117, v200, v201
	v_lshlrev_b32_e32 v200, 16, v118
	v_and_b32_e32 v201, 0xffff0000, v118
	v_mul_f32_e32 v200, v35, v200
	v_mul_f32_e32 v201, v35, v201
	v_cvt_pk_bf16_f32 v118, v200, v201
	v_lshlrev_b32_e32 v200, 16, v119
	v_and_b32_e32 v201, 0xffff0000, v119
	v_mul_f32_e32 v200, v35, v200
	v_mul_f32_e32 v201, v35, v201
	v_cvt_pk_bf16_f32 v119, v200, v201
	global_store_dwordx4 v[182:183], v[116:119], off offset:3072
	v_lshlrev_b32_e32 v200, 16, v120
	v_and_b32_e32 v201, 0xffff0000, v120
	v_mul_f32_e32 v200, v36, v200
	v_mul_f32_e32 v201, v36, v201
	v_cvt_pk_bf16_f32 v120, v200, v201
	v_lshlrev_b32_e32 v200, 16, v121
	v_and_b32_e32 v201, 0xffff0000, v121
	v_mul_f32_e32 v200, v36, v200
	v_mul_f32_e32 v201, v36, v201
	v_cvt_pk_bf16_f32 v121, v200, v201
	v_lshlrev_b32_e32 v200, 16, v122
	v_and_b32_e32 v201, 0xffff0000, v122
	v_mul_f32_e32 v200, v36, v200
	v_mul_f32_e32 v201, v36, v201
	v_cvt_pk_bf16_f32 v122, v200, v201
	v_lshlrev_b32_e32 v200, 16, v123
	v_and_b32_e32 v201, 0xffff0000, v123
	v_mul_f32_e32 v200, v36, v200
	v_mul_f32_e32 v201, v36, v201
	v_cvt_pk_bf16_f32 v123, v200, v201
	global_store_dwordx4 v[196:197], v[120:123], off
	v_lshlrev_b32_e32 v200, 16, v124
	v_and_b32_e32 v201, 0xffff0000, v124
	v_mul_f32_e32 v200, v37, v200
	v_mul_f32_e32 v201, v37, v201
	v_cvt_pk_bf16_f32 v124, v200, v201
	v_lshlrev_b32_e32 v200, 16, v125
	v_and_b32_e32 v201, 0xffff0000, v125
	v_mul_f32_e32 v200, v37, v200
	v_mul_f32_e32 v201, v37, v201
	v_cvt_pk_bf16_f32 v125, v200, v201
	v_lshlrev_b32_e32 v200, 16, v126
	v_and_b32_e32 v201, 0xffff0000, v126
	v_mul_f32_e32 v200, v37, v200
	v_mul_f32_e32 v201, v37, v201
	v_cvt_pk_bf16_f32 v126, v200, v201
	v_lshlrev_b32_e32 v200, 16, v127
	v_and_b32_e32 v201, 0xffff0000, v127
	v_mul_f32_e32 v200, v37, v200
	v_mul_f32_e32 v201, v37, v201
	v_cvt_pk_bf16_f32 v127, v200, v201
	global_store_dwordx4 v[196:197], v[124:127], off offset:1024
	v_lshlrev_b32_e32 v200, 16, v128
	v_and_b32_e32 v201, 0xffff0000, v128
	v_mul_f32_e32 v200, v38, v200
	v_mul_f32_e32 v201, v38, v201
	v_cvt_pk_bf16_f32 v128, v200, v201
	v_lshlrev_b32_e32 v200, 16, v129
	v_and_b32_e32 v201, 0xffff0000, v129
	v_mul_f32_e32 v200, v38, v200
	v_mul_f32_e32 v201, v38, v201
	v_cvt_pk_bf16_f32 v129, v200, v201
	v_lshlrev_b32_e32 v200, 16, v130
	v_and_b32_e32 v201, 0xffff0000, v130
	v_mul_f32_e32 v200, v38, v200
	v_mul_f32_e32 v201, v38, v201
	v_cvt_pk_bf16_f32 v130, v200, v201
	v_lshlrev_b32_e32 v200, 16, v131
	v_and_b32_e32 v201, 0xffff0000, v131
	v_mul_f32_e32 v200, v38, v200
	v_mul_f32_e32 v201, v38, v201
	v_cvt_pk_bf16_f32 v131, v200, v201
	global_store_dwordx4 v[196:197], v[128:131], off offset:2048
	v_lshlrev_b32_e32 v200, 16, v132
	v_and_b32_e32 v201, 0xffff0000, v132
	v_mul_f32_e32 v200, v39, v200
	v_mul_f32_e32 v201, v39, v201
	v_cvt_pk_bf16_f32 v132, v200, v201
	v_lshlrev_b32_e32 v200, 16, v133
	v_and_b32_e32 v201, 0xffff0000, v133
	v_mul_f32_e32 v200, v39, v200
	v_mul_f32_e32 v201, v39, v201
	v_cvt_pk_bf16_f32 v133, v200, v201
	v_lshlrev_b32_e32 v200, 16, v134
	v_and_b32_e32 v201, 0xffff0000, v134
	v_mul_f32_e32 v200, v39, v200
	v_mul_f32_e32 v201, v39, v201
	v_cvt_pk_bf16_f32 v134, v200, v201
	v_lshlrev_b32_e32 v200, 16, v135
	v_and_b32_e32 v201, 0xffff0000, v135
	v_mul_f32_e32 v200, v39, v200
	v_mul_f32_e32 v201, v39, v201
	v_cvt_pk_bf16_f32 v135, v200, v201
	global_store_dwordx4 v[196:197], v[132:135], off offset:3072
	s_waitcnt vmcnt(24)
	v_lshlrev_b32_e32 v200, 16, v136
	v_and_b32_e32 v201, 0xffff0000, v136
	v_mul_f32_e32 v200, v0, v200
	v_mul_f32_e32 v201, v0, v201
	v_cvt_pk_bf16_f32 v136, v200, v201
	v_lshlrev_b32_e32 v200, 16, v137
	v_and_b32_e32 v201, 0xffff0000, v137
	v_mul_f32_e32 v200, v0, v200
	v_mul_f32_e32 v201, v0, v201
	v_cvt_pk_bf16_f32 v137, v200, v201
	v_lshlrev_b32_e32 v200, 16, v138
	v_and_b32_e32 v201, 0xffff0000, v138
	v_mul_f32_e32 v200, v0, v200
	v_mul_f32_e32 v201, v0, v201
	v_cvt_pk_bf16_f32 v138, v200, v201
	v_lshlrev_b32_e32 v200, 16, v139
	v_and_b32_e32 v201, 0xffff0000, v139
	v_mul_f32_e32 v200, v0, v200
	v_mul_f32_e32 v201, v0, v201
	v_cvt_pk_bf16_f32 v139, v200, v201
	global_store_dwordx4 v[186:187], v[136:139], off
	v_lshlrev_b32_e32 v200, 16, v140
	v_and_b32_e32 v201, 0xffff0000, v140
	v_mul_f32_e32 v200, v1, v200
	v_mul_f32_e32 v201, v1, v201
	v_cvt_pk_bf16_f32 v140, v200, v201
	v_lshlrev_b32_e32 v200, 16, v141
	v_and_b32_e32 v201, 0xffff0000, v141
	v_mul_f32_e32 v200, v1, v200
	v_mul_f32_e32 v201, v1, v201
	v_cvt_pk_bf16_f32 v141, v200, v201
	v_lshlrev_b32_e32 v200, 16, v142
	v_and_b32_e32 v201, 0xffff0000, v142
	v_mul_f32_e32 v200, v1, v200
	v_mul_f32_e32 v201, v1, v201
	v_cvt_pk_bf16_f32 v142, v200, v201
	v_lshlrev_b32_e32 v200, 16, v143
	v_and_b32_e32 v201, 0xffff0000, v143
	v_mul_f32_e32 v200, v1, v200
	v_mul_f32_e32 v201, v1, v201
	v_cvt_pk_bf16_f32 v143, v200, v201
	global_store_dwordx4 v[186:187], v[140:143], off offset:1024
	v_lshlrev_b32_e32 v200, 16, v144
	v_and_b32_e32 v201, 0xffff0000, v144
	v_mul_f32_e32 v200, v2, v200
	v_mul_f32_e32 v201, v2, v201
	v_cvt_pk_bf16_f32 v144, v200, v201
	v_lshlrev_b32_e32 v200, 16, v145
	v_and_b32_e32 v201, 0xffff0000, v145
	v_mul_f32_e32 v200, v2, v200
	v_mul_f32_e32 v201, v2, v201
	v_cvt_pk_bf16_f32 v145, v200, v201
	v_lshlrev_b32_e32 v200, 16, v146
	v_and_b32_e32 v201, 0xffff0000, v146
	v_mul_f32_e32 v200, v2, v200
	v_mul_f32_e32 v201, v2, v201
	v_cvt_pk_bf16_f32 v146, v200, v201
	v_lshlrev_b32_e32 v200, 16, v147
	v_and_b32_e32 v201, 0xffff0000, v147
	v_mul_f32_e32 v200, v2, v200
	v_mul_f32_e32 v201, v2, v201
	v_cvt_pk_bf16_f32 v147, v200, v201
	global_store_dwordx4 v[186:187], v[144:147], off offset:2048
	v_lshlrev_b32_e32 v200, 16, v148
	v_and_b32_e32 v201, 0xffff0000, v148
	v_mul_f32_e32 v200, v3, v200
	v_mul_f32_e32 v201, v3, v201
	v_cvt_pk_bf16_f32 v148, v200, v201
	v_lshlrev_b32_e32 v200, 16, v149
	v_and_b32_e32 v201, 0xffff0000, v149
	v_mul_f32_e32 v200, v3, v200
	v_mul_f32_e32 v201, v3, v201
	v_cvt_pk_bf16_f32 v149, v200, v201
	v_lshlrev_b32_e32 v200, 16, v150
	v_and_b32_e32 v201, 0xffff0000, v150
	v_mul_f32_e32 v200, v3, v200
	v_mul_f32_e32 v201, v3, v201
	v_cvt_pk_bf16_f32 v150, v200, v201
	v_lshlrev_b32_e32 v200, 16, v151
	v_and_b32_e32 v201, 0xffff0000, v151
	v_mul_f32_e32 v200, v3, v200
	v_mul_f32_e32 v201, v3, v201
	v_cvt_pk_bf16_f32 v151, v200, v201
	global_store_dwordx4 v[186:187], v[148:151], off offset:3072
	v_lshlrev_b32_e32 v200, 16, v152
	v_and_b32_e32 v201, 0xffff0000, v152
	v_mul_f32_e32 v200, v168, v200
	v_mul_f32_e32 v201, v168, v201
	v_cvt_pk_bf16_f32 v152, v200, v201
	v_lshlrev_b32_e32 v200, 16, v153
	v_and_b32_e32 v201, 0xffff0000, v153
	v_mul_f32_e32 v200, v168, v200
	v_mul_f32_e32 v201, v168, v201
	v_cvt_pk_bf16_f32 v153, v200, v201
	v_lshlrev_b32_e32 v200, 16, v154
	v_and_b32_e32 v201, 0xffff0000, v154
	v_mul_f32_e32 v200, v168, v200
	v_mul_f32_e32 v201, v168, v201
	v_cvt_pk_bf16_f32 v154, v200, v201
	v_lshlrev_b32_e32 v200, 16, v155
	v_and_b32_e32 v201, 0xffff0000, v155
	v_mul_f32_e32 v200, v168, v200
	v_mul_f32_e32 v201, v168, v201
	v_cvt_pk_bf16_f32 v155, v200, v201
	global_store_dwordx4 v[198:199], v[152:155], off
	v_lshlrev_b32_e32 v200, 16, v156
	v_and_b32_e32 v201, 0xffff0000, v156
	v_mul_f32_e32 v200, v169, v200
	v_mul_f32_e32 v201, v169, v201
	v_cvt_pk_bf16_f32 v156, v200, v201
	v_lshlrev_b32_e32 v200, 16, v157
	v_and_b32_e32 v201, 0xffff0000, v157
	v_mul_f32_e32 v200, v169, v200
	v_mul_f32_e32 v201, v169, v201
	v_cvt_pk_bf16_f32 v157, v200, v201
	v_lshlrev_b32_e32 v200, 16, v158
	v_and_b32_e32 v201, 0xffff0000, v158
	v_mul_f32_e32 v200, v169, v200
	v_mul_f32_e32 v201, v169, v201
	v_cvt_pk_bf16_f32 v158, v200, v201
	v_lshlrev_b32_e32 v200, 16, v159
	v_and_b32_e32 v201, 0xffff0000, v159
	v_mul_f32_e32 v200, v169, v200
	v_mul_f32_e32 v201, v169, v201
	v_cvt_pk_bf16_f32 v159, v200, v201
	global_store_dwordx4 v[198:199], v[156:159], off offset:1024
	v_lshlrev_b32_e32 v200, 16, v160
	v_and_b32_e32 v201, 0xffff0000, v160
	v_mul_f32_e32 v200, v170, v200
	v_mul_f32_e32 v201, v170, v201
	v_cvt_pk_bf16_f32 v160, v200, v201
	v_lshlrev_b32_e32 v200, 16, v161
	v_and_b32_e32 v201, 0xffff0000, v161
	v_mul_f32_e32 v200, v170, v200
	v_mul_f32_e32 v201, v170, v201
	v_cvt_pk_bf16_f32 v161, v200, v201
	v_lshlrev_b32_e32 v200, 16, v162
	v_and_b32_e32 v201, 0xffff0000, v162
	v_mul_f32_e32 v200, v170, v200
	v_mul_f32_e32 v201, v170, v201
	v_cvt_pk_bf16_f32 v162, v200, v201
	v_lshlrev_b32_e32 v200, 16, v163
	v_and_b32_e32 v201, 0xffff0000, v163
	v_mul_f32_e32 v200, v170, v200
	v_mul_f32_e32 v201, v170, v201
	v_cvt_pk_bf16_f32 v163, v200, v201
	global_store_dwordx4 v[198:199], v[160:163], off offset:2048
	v_lshlrev_b32_e32 v200, 16, v164
	v_and_b32_e32 v201, 0xffff0000, v164
	v_mul_f32_e32 v200, v171, v200
	v_mul_f32_e32 v201, v171, v201
	v_cvt_pk_bf16_f32 v164, v200, v201
	v_lshlrev_b32_e32 v200, 16, v165
	v_and_b32_e32 v201, 0xffff0000, v165
	v_mul_f32_e32 v200, v171, v200
	v_mul_f32_e32 v201, v171, v201
	v_cvt_pk_bf16_f32 v165, v200, v201
	v_lshlrev_b32_e32 v200, 16, v166
	v_and_b32_e32 v201, 0xffff0000, v166
	v_mul_f32_e32 v200, v171, v200
	v_mul_f32_e32 v201, v171, v201
	v_cvt_pk_bf16_f32 v166, v200, v201
	v_lshlrev_b32_e32 v200, 16, v167
	v_and_b32_e32 v201, 0xffff0000, v167
	v_mul_f32_e32 v200, v171, v200
	v_mul_f32_e32 v201, v171, v201
	v_cvt_pk_bf16_f32 v167, v200, v201
	global_store_dwordx4 v[198:199], v[164:167], off offset:3072
	s_lshl_b32 s4, s2, 2
	s_add_i32 s26, s26, s4
	s_branch .Lgn_top
.Lgn_exit:
	s_cmpk_gt_i32 s26, 0x2007
	s_cbranch_scc1 .LBB0_252
	s_branch .LBB0_220

.LBB0_690:
	s_ashr_i32 s11, s0, 3
	s_lshl_b32 s42, s11, 8
	s_and_b32 s9, s2, 0x70
	v_or_b32_e32 v1, s42, v38
	v_or_b32_e32 v1, s9, v1
	s_ashr_i32 s43, s42, 31
	v_mul_lo_u32 v2, s27, v1
	s_mul_i32 s9, s26, s43
	v_mad_u64_u32 v[32:33], s[44:45], s26, v1, v[30:31]
	v_add3_u32 v33, v2, v33, s9
	v_mov_b32_e32 v2, 0x100
	v_lshl_or_b32 v1, v1, 1, v2
	v_mov_b32_e32 v0, v173
	v_mov_b32_e32 v4, v173
	s_mul_i32 s9, s72, s43
	v_mad_u64_u32 v[34:35], s[44:45], s72, v1, v[30:31]
	s_mov_b32 s8, 0
	v_add_u32_e32 v35, s9, v35
	v_mov_b64_e32 v[36:37], v[8:9]
	v_mov_b32_e32 v1, v0
	v_mov_b32_e32 v2, v0
	v_mov_b32_e32 v3, v0
	v_mov_b32_e32 v5, v4
	v_mov_b32_e32 v6, v4
	v_mov_b32_e32 v7, v4
	s_lshr_b32 s8, s1, 5
.Lthin_chunk:
	s_cmp_ge_u32 s8, 8
	s_cbranch_scc1 .Lthin_L0
	s_sub_u32 s9, 8, s8
	s_lshl_b32 s9, s9, 6
	s_sub_u32 s44, 0, s9
	s_mov_b32 s45, -1
	v_lshl_add_u64 v[32:33], v[32:33], 0, s[44:45]
	v_lshl_add_u64 v[34:35], v[34:35], 0, s[44:45]
	v_lshl_add_u64 v[36:37], v[36:37], 0, s[44:45]
	s_cmp_eq_u32 s8, 7
	s_cbranch_scc1 .Lthin_L1
	s_cmp_eq_u32 s8, 6
	s_cbranch_scc1 .Lthin_L2
	s_cmp_eq_u32 s8, 5
	s_cbranch_scc1 .Lthin_L3
	s_cmp_eq_u32 s8, 4
	s_cbranch_scc1 .Lthin_L4
	s_cmp_eq_u32 s8, 3
	s_cbranch_scc1 .Lthin_L5
	s_cmp_eq_u32 s8, 2
	s_cbranch_scc1 .Lthin_L6
	s_cmp_eq_u32 s8, 1
	s_cbranch_scc1 .Lthin_L7
	s_branch .Lthin_done
.Lthin_L0:
	global_load_dwordx4 v[44:47], v[32:33], off
	global_load_dwordx4 v[48:51], v[36:37], off
	global_load_dwordx4 v[52:55], v[34:35], off
.Lthin_L1:
	global_load_dwordx4 v[56:59], v[32:33], off offset:64
	global_load_dwordx4 v[60:63], v[36:37], off offset:64
	global_load_dwordx4 v[64:67], v[34:35], off offset:64
.Lthin_L2:
	global_load_dwordx4 v[68:71], v[32:33], off offset:128
	global_load_dwordx4 v[72:75], v[36:37], off offset:128
	global_load_dwordx4 v[76:79], v[34:35], off offset:128
.Lthin_L3:
	global_load_dwordx4 v[80:83], v[32:33], off offset:192
	global_load_dwordx4 v[84:87], v[36:37], off offset:192
	global_load_dwordx4 v[88:91], v[34:35], off offset:192
.Lthin_L4:
	global_load_dwordx4 v[92:95], v[32:33], off offset:256
	global_load_dwordx4 v[96:99], v[36:37], off offset:256
	global_load_dwordx4 v[100:103], v[34:35], off offset:256
.Lthin_L5:
	global_load_dwordx4 v[104:107], v[32:33], off offset:320
	global_load_dwordx4 v[108:111], v[36:37], off offset:320
	global_load_dwordx4 v[112:115], v[34:35], off offset:320
.Lthin_L6:
	global_load_dwordx4 v[116:119], v[32:33], off offset:384
	global_load_dwordx4 v[120:123], v[36:37], off offset:384
	global_load_dwordx4 v[124:127], v[34:35], off offset:384
.Lthin_L7:
	global_load_dwordx4 v[128:131], v[32:33], off offset:448
	global_load_dwordx4 v[132:135], v[36:37], off offset:448
	global_load_dwordx4 v[136:139], v[34:35], off offset:448
	s_cmp_ge_u32 s8, 8
	s_cbranch_scc1 .Lthin_C0
	s_cmp_eq_u32 s8, 7
	s_cbranch_scc1 .Lthin_C1
	s_cmp_eq_u32 s8, 6
	s_cbranch_scc1 .Lthin_C2
	s_cmp_eq_u32 s8, 5
	s_cbranch_scc1 .Lthin_C3
	s_cmp_eq_u32 s8, 4
	s_cbranch_scc1 .Lthin_C4
	s_cmp_eq_u32 s8, 3
	s_cbranch_scc1 .Lthin_C5
	s_cmp_eq_u32 s8, 2
	s_cbranch_scc1 .Lthin_C6
	s_cmp_eq_u32 s8, 1
	s_cbranch_scc1 .Lthin_C7
.Lthin_C0:
	s_waitcnt vmcnt(21)
	v_mfma_f32_16x16x32_bf16 v[0:3], v[44:47], v[48:51], v[0:3]
	v_mfma_f32_16x16x32_bf16 v[4:7], v[52:55], v[48:51], v[4:7]
.Lthin_C1:
	s_waitcnt vmcnt(18)
	v_mfma_f32_16x16x32_bf16 v[0:3], v[56:59], v[60:63], v[0:3]
	v_mfma_f32_16x16x32_bf16 v[4:7], v[64:67], v[60:63], v[4:7]
.Lthin_C2:
	s_waitcnt vmcnt(15)
	v_mfma_f32_16x16x32_bf16 v[0:3], v[68:71], v[72:75], v[0:3]
	v_mfma_f32_16x16x32_bf16 v[4:7], v[76:79], v[72:75], v[4:7]
.Lthin_C3:
	s_waitcnt vmcnt(12)
	v_mfma_f32_16x16x32_bf16 v[0:3], v[80:83], v[84:87], v[0:3]
	v_mfma_f32_16x16x32_bf16 v[4:7], v[88:91], v[84:87], v[4:7]
.Lthin_C4:
	s_waitcnt vmcnt(9)
	v_mfma_f32_16x16x32_bf16 v[0:3], v[92:95], v[96:99], v[0:3]
	v_mfma_f32_16x16x32_bf16 v[4:7], v[100:103], v[96:99], v[4:7]
.Lthin_C5:
	s_waitcnt vmcnt(6)
	v_mfma_f32_16x16x32_bf16 v[0:3], v[104:107], v[108:111], v[0:3]
	v_mfma_f32_16x16x32_bf16 v[4:7], v[112:115], v[108:111], v[4:7]
.Lthin_C6:
	s_waitcnt vmcnt(3)
	v_mfma_f32_16x16x32_bf16 v[0:3], v[116:119], v[120:123], v[0:3]
	v_mfma_f32_16x16x32_bf16 v[4:7], v[124:127], v[120:123], v[4:7]
.Lthin_C7:
	s_waitcnt vmcnt(0)
	v_mfma_f32_16x16x32_bf16 v[0:3], v[128:131], v[132:135], v[0:3]
	v_mfma_f32_16x16x32_bf16 v[4:7], v[136:139], v[132:135], v[4:7]
	s_cmp_le_u32 s8, 8
	s_cbranch_scc1 .Lthin_done
	s_sub_u32 s8, s8, 8
	s_mov_b64 s[44:45], 0x200
	v_lshl_add_u64 v[32:33], v[32:33], 0, s[44:45]
	v_lshl_add_u64 v[34:35], v[34:35], 0, s[44:45]
	v_lshl_add_u64 v[36:37], v[36:37], 0, s[44:45]
	s_branch .Lthin_chunk
.Lthin_done:
	s_nop 7
	s_nop 2
	ds_write2st64_b32 v42, v0, v1 offset1:1
	s_nop 2
	ds_write2st64_b32 v42, v4, v5 offset0:4 offset1:5
	ds_write2st64_b32 v42, v2, v3 offset0:2 offset1:3
	ds_write2st64_b32 v42, v6, v7 offset0:6 offset1:7
	s_waitcnt lgkmcnt(0)
	s_barrier
	s_and_saveexec_b64 s[8:9], s[40:41]
	s_cbranch_execz .LBB0_689
	ds_read2st64_b32 v[0:1], v40 offset1:8
	ds_read2st64_b32 v[2:3], v41 offset0:4 offset1:12
	s_lshl_b32 s15, s0, 4
	s_and_b32 s15, s15, 0x70
	s_mov_b64 s[44:45], -1
	s_waitcnt lgkmcnt(1)
	v_add_f32_e32 v0, 0, v0
	s_waitcnt lgkmcnt(0)
	v_add_f32_e32 v2, 0, v2
	v_add_f32_e32 v4, v0, v1
	v_add_f32_e32 v5, v2, v3
	ds_read2st64_b32 v[0:1], v40 offset0:16 offset1:24
	ds_read2st64_b32 v[2:3], v41 offset0:20 offset1:28
	s_cmp_lt_i32 s96, 2
	s_waitcnt lgkmcnt(1)
	v_add_f32_e32 v0, v4, v0
	s_waitcnt lgkmcnt(0)
	v_add_f32_e32 v2, v5, v2
	v_add_f32_e32 v4, v0, v1
	v_add_f32_e32 v5, v2, v3
	ds_read2st64_b32 v[0:1], v40 offset0:32 offset1:40
	ds_read2st64_b32 v[2:3], v41 offset0:36 offset1:44
	s_waitcnt lgkmcnt(1)
	v_add_f32_e32 v0, v4, v0
	s_waitcnt lgkmcnt(0)
	v_add_f32_e32 v2, v5, v2
	v_add_f32_e32 v4, v0, v1
	v_add_f32_e32 v5, v2, v3
	ds_read2st64_b32 v[0:1], v40 offset0:48 offset1:56
	ds_read2st64_b32 v[2:3], v41 offset0:52 offset1:60
	s_waitcnt lgkmcnt(1)
	v_add_f32_e32 v0, v4, v0
	s_waitcnt lgkmcnt(0)
	v_add_f32_e32 v2, v5, v2
	v_add_f32_e32 v5, v0, v1
	v_add_f32_e32 v4, v2, v3
	v_add_u32_e32 v0, s15, v39
	s_cbranch_scc1 .LBB0_707
	s_cmp_gt_i32 s96, 2
	s_cbranch_scc0 .LBB0_704
	s_and_b32 s15, s0, 0xffffffe0
	s_cmp_lg_u32 s15, 32
	s_cbranch_scc0 .LBB0_701
	v_and_b32_e32 v1, 63, v0
	v_mov_b32_e32 v3, 0x100000
	v_lshl_or_b32 v3, v1, 2, v3
	global_load_dword v32, v3, s[4:5]
	s_nop 0
	global_load_dword v3, v3, s[6:7]
	s_lshl_b32 s15, s11, 1
	s_add_i32 s17, s15, -16
	s_cmp_lt_i32 s11, 4
	s_cselect_b32 s15, s15, s17
	v_lshrrev_b32_e32 v2, 6, v0
	v_add_lshl_u32 v2, s15, v2, 7
	s_cmp_gt_i32 s11, 3
	v_lshlrev_b32_e32 v172, 1, v1
	s_waitcnt vmcnt(0)
	v_mul_f32_e32 v6, v4, v3
	v_mul_f32_e32 v7, v5, v3
	v_fma_f32 v6, v5, v32, -v6
	v_fmac_f32_e32 v7, v4, v32
	v_ashrrev_i32_e32 v3, 31, v2
	v_cvt_pk_bf16_f32 v32, v6, s0
	v_cvt_pk_bf16_f32 v33, v7, s0
	s_cbranch_scc0 .LBB0_698
	v_lshl_add_u64 v[34:35], v[2:3], 1, v[10:11]
	v_lshl_add_u64 v[34:35], v[34:35], 0, v[172:173]
	global_store_short v[34:35], v32, off
	global_store_short v[34:35], v33, off offset:128
	s_mov_b64 s[44:45], 0

	.amdhsa_kernel _Z8yoco_fwd6Paramsii
		.amdhsa_group_segment_fixed_size 0
		.amdhsa_private_segment_fixed_size 0
		.amdhsa_kernarg_size 472
		.amdhsa_user_sgpr_count 2
		.amdhsa_user_sgpr_dispatch_ptr 0
		.amdhsa_user_sgpr_queue_ptr 0
		.amdhsa_user_sgpr_kernarg_segment_ptr 1
		.amdhsa_user_sgpr_dispatch_id 0
		.amdhsa_user_sgpr_kernarg_preload_length 0
		.amdhsa_user_sgpr_kernarg_preload_offset 0
		.amdhsa_user_sgpr_private_segment_size 0
		.amdhsa_uses_dynamic_stack 0
		.amdhsa_enable_private_segment 0
		.amdhsa_system_sgpr_workgroup_id_x 1
		.amdhsa_system_sgpr_workgroup_id_y 0
		.amdhsa_system_sgpr_workgroup_id_z 0
		.amdhsa_system_sgpr_workgroup_info 0
		.amdhsa_system_vgpr_workitem_id 2
		.amdhsa_next_free_vgpr 256
		.amdhsa_next_free_sgpr 102
		.amdhsa_accum_offset 256
		.amdhsa_reserve_vcc 1
		.amdhsa_float_round_mode_32 0
		.amdhsa_float_round_mode_16_64 0
		.amdhsa_float_denorm_mode_32 3
		.amdhsa_float_denorm_mode_16_64 3
		.amdhsa_dx10_clamp 1
		.amdhsa_ieee_mode 1
		.amdhsa_fp16_overflow 0
		.amdhsa_tg_split 0
		.amdhsa_exception_fp_ieee_invalid_op 0
		.amdhsa_exception_fp_denorm_src 0
		.amdhsa_exception_fp_ieee_div_zero 0
		.amdhsa_exception_fp_ieee_overflow 0
		.amdhsa_exception_fp_ieee_underflow 0
		.amdhsa_exception_fp_ieee_inexact 0
		.amdhsa_exception_int_div_zero 0
	.end_amdhsa_kernel

amdhsa.kernels:
  - .agpr_count:     0
    .args:
      - .offset:         0
        .size:           208
        .value_kind:     by_value
      - .offset:         208
        .size:           4
        .value_kind:     by_value
      - .offset:         212
        .size:           4
        .value_kind:     by_value
      - .offset:         216
        .size:           4
        .value_kind:     hidden_block_count_x
      - .offset:         220
        .size:           4
        .value_kind:     hidden_block_count_y
      - .offset:         224
        .size:           4
        .value_kind:     hidden_block_count_z
      - .offset:         228
        .size:           2
        .value_kind:     hidden_group_size_x
      - .offset:         230
        .size:           2
        .value_kind:     hidden_group_size_y
      - .offset:         232
        .size:           2
        .value_kind:     hidden_group_size_z
      - .offset:         234
        .size:           2
        .value_kind:     hidden_remainder_x
      - .offset:         236
        .size:           2
        .value_kind:     hidden_remainder_y
      - .offset:         238
        .size:           2
        .value_kind:     hidden_remainder_z
      - .offset:         256
        .size:           8
        .value_kind:     hidden_global_offset_x
      - .offset:         264
        .size:           8
        .value_kind:     hidden_global_offset_y
      - .offset:         272
        .size:           8
        .value_kind:     hidden_global_offset_z
      - .offset:         280
        .size:           2
        .value_kind:     hidden_grid_dims
      - .offset:         304
        .size:           8
        .value_kind:     hidden_multigrid_sync_arg
      - .offset:         336
        .size:           4
        .value_kind:     hidden_dynamic_lds_size
    .group_segment_fixed_size: 0
    .kernarg_segment_align: 8
    .kernarg_segment_size: 472
    .language:       OpenCL C
    .language_version:
      - 2
      - 0
    .max_flat_workgroup_size: 512
    .name:           _Z8yoco_fwd6Paramsii
    .private_segment_fixed_size: 0
    .sgpr_count:     108
    .sgpr_spill_count: 177
    .symbol:         _Z8yoco_fwd6Paramsii.kd
    .uniform_work_group_size: 1
    .uses_dynamic_stack: false
    .vgpr_count:     256
    .vgpr_spill_count: 0
    .wavefront_size: 64
